# v17 with system-scope (sc0 sc1) partial-sum stores and loads instead of an L2 write-back / invalidate around the hand-over
# baseline (speedup 1.0000x reference)
.LBB0_273:
	s_cmp_eq_u32 s24, 18
	s_cbranch_scc0 .Lsk_none
	s_cmp_eq_u32 s80, 0x100
	s_cbranch_scc0 .Lsk_none
	s_cmp_eq_u32 s0, 5
	s_cbranch_scc0 .Lsk_none
	s_sub_u32 s2, s30, 0x28700000
	s_subb_u32 s3, s31, 0
	v_readfirstlane_b32 s50, v160
	s_lshr_b32 s50, s50, 6
	s_and_b32 s51, s12, 0x7f
	v_lshlrev_b32_e32 v250, 4, v197
	v_mov_b32_e32 v251, 1
	s_lshl_b32 s90, s51, 18
	s_lshl_b32 s91, s50, 15
	s_add_u32 s90, s90, s91
	s_add_u32 s90, s90, 0x1fb00000
	s_lshl_b32 s51, s51, 2
	s_add_u32 s100, s2, s90
	s_addc_u32 s101, s3, 0
	s_add_u32 s2, s2, s51
	s_addc_u32 s3, s3, 0
	s_add_u32 s2, s2, 0x8000
	s_addc_u32 s3, s3, 0
	s_cmp_lt_u32 s12, 0x80
	s_cbranch_scc1 .Lsk_owner
	global_store_dwordx4 v250, v[0:3], s[100:101] sc0 sc1
	global_store_dwordx4 v250, v[4:7], s[100:101] offset:1024 sc0 sc1
	global_store_dwordx4 v250, v[8:11], s[100:101] offset:2048 sc0 sc1
	global_store_dwordx4 v250, v[12:15], s[100:101] offset:3072 sc0 sc1
	s_add_u32 s100, s100, 0x1000
	s_addc_u32 s101, s101, 0
	global_store_dwordx4 v250, v[16:19], s[100:101] sc0 sc1
	global_store_dwordx4 v250, v[20:23], s[100:101] offset:1024 sc0 sc1
	global_store_dwordx4 v250, v[24:27], s[100:101] offset:2048 sc0 sc1
	global_store_dwordx4 v250, v[28:31], s[100:101] offset:3072 sc0 sc1
	s_add_u32 s100, s100, 0x1000
	s_addc_u32 s101, s101, 0
	global_store_dwordx4 v250, v[32:35], s[100:101] sc0 sc1
	global_store_dwordx4 v250, v[36:39], s[100:101] offset:1024 sc0 sc1
	global_store_dwordx4 v250, v[40:43], s[100:101] offset:2048 sc0 sc1
	global_store_dwordx4 v250, v[44:47], s[100:101] offset:3072 sc0 sc1
	s_add_u32 s100, s100, 0x1000
	s_addc_u32 s101, s101, 0
	global_store_dwordx4 v250, v[48:51], s[100:101] sc0 sc1
	global_store_dwordx4 v250, v[52:55], s[100:101] offset:1024 sc0 sc1
	global_store_dwordx4 v250, v[56:59], s[100:101] offset:2048 sc0 sc1
	global_store_dwordx4 v250, v[60:63], s[100:101] offset:3072 sc0 sc1
	s_add_u32 s100, s100, 0x1000
	s_addc_u32 s101, s101, 0
	global_store_dwordx4 v250, v[64:67], s[100:101] sc0 sc1
	global_store_dwordx4 v250, v[68:71], s[100:101] offset:1024 sc0 sc1
	global_store_dwordx4 v250, v[72:75], s[100:101] offset:2048 sc0 sc1
	global_store_dwordx4 v250, v[76:79], s[100:101] offset:3072 sc0 sc1
	s_add_u32 s100, s100, 0x1000
	s_addc_u32 s101, s101, 0
	global_store_dwordx4 v250, v[80:83], s[100:101] sc0 sc1
	global_store_dwordx4 v250, v[84:87], s[100:101] offset:1024 sc0 sc1
	global_store_dwordx4 v250, v[88:91], s[100:101] offset:2048 sc0 sc1
	global_store_dwordx4 v250, v[92:95], s[100:101] offset:3072 sc0 sc1
	s_add_u32 s100, s100, 0x1000
	s_addc_u32 s101, s101, 0
	global_store_dwordx4 v250, v[96:99], s[100:101] sc0 sc1
	global_store_dwordx4 v250, v[100:103], s[100:101] offset:1024 sc0 sc1
	global_store_dwordx4 v250, v[104:107], s[100:101] offset:2048 sc0 sc1
	global_store_dwordx4 v250, v[108:111], s[100:101] offset:3072 sc0 sc1
	s_add_u32 s100, s100, 0x1000
	s_addc_u32 s101, s101, 0
	global_store_dwordx4 v250, v[112:115], s[100:101] sc0 sc1
	global_store_dwordx4 v250, v[116:119], s[100:101] offset:1024 sc0 sc1
	global_store_dwordx4 v250, v[120:123], s[100:101] offset:2048 sc0 sc1
	global_store_dwordx4 v250, v[124:127], s[100:101] offset:3072 sc0 sc1
	s_waitcnt vmcnt(0)
	s_barrier
	s_cmp_eq_u32 s50, 0
	s_cbranch_scc0 .LBB0_492
	s_mov_b64 s[90:91], exec
	s_mov_b64 exec, 1
	global_atomic_add v157, v251, s[2:3]
	s_mov_b64 exec, s[90:91]
	s_waitcnt vmcnt(0)
	s_branch .LBB0_492

.Lsk_go:
	global_load_dwordx4 v[232:235], v250, s[100:101] sc0 sc1
	global_load_dwordx4 v[236:239], v250, s[100:101] offset:1024 sc0 sc1
	global_load_dwordx4 v[240:243], v250, s[100:101] offset:2048 sc0 sc1
	global_load_dwordx4 v[244:247], v250, s[100:101] offset:3072 sc0 sc1
	s_add_u32 s100, s100, 0x1000
	s_addc_u32 s101, s101, 0
	s_waitcnt vmcnt(0)
	v_pk_add_f32 v[0:1], v[0:1], v[232:233]
	v_pk_add_f32 v[2:3], v[2:3], v[234:235]
	v_pk_add_f32 v[4:5], v[4:5], v[236:237]
	v_pk_add_f32 v[6:7], v[6:7], v[238:239]
	v_pk_add_f32 v[8:9], v[8:9], v[240:241]
	v_pk_add_f32 v[10:11], v[10:11], v[242:243]
	v_pk_add_f32 v[12:13], v[12:13], v[244:245]
	v_pk_add_f32 v[14:15], v[14:15], v[246:247]
	global_load_dwordx4 v[232:235], v250, s[100:101] sc0 sc1
	global_load_dwordx4 v[236:239], v250, s[100:101] offset:1024 sc0 sc1
	global_load_dwordx4 v[240:243], v250, s[100:101] offset:2048 sc0 sc1
	global_load_dwordx4 v[244:247], v250, s[100:101] offset:3072 sc0 sc1
	s_add_u32 s100, s100, 0x1000
	s_addc_u32 s101, s101, 0
	s_waitcnt vmcnt(0)
	v_pk_add_f32 v[16:17], v[16:17], v[232:233]
	v_pk_add_f32 v[18:19], v[18:19], v[234:235]
	v_pk_add_f32 v[20:21], v[20:21], v[236:237]
	v_pk_add_f32 v[22:23], v[22:23], v[238:239]
	v_pk_add_f32 v[24:25], v[24:25], v[240:241]
	v_pk_add_f32 v[26:27], v[26:27], v[242:243]
	v_pk_add_f32 v[28:29], v[28:29], v[244:245]
	v_pk_add_f32 v[30:31], v[30:31], v[246:247]
	global_load_dwordx4 v[232:235], v250, s[100:101] sc0 sc1
	global_load_dwordx4 v[236:239], v250, s[100:101] offset:1024 sc0 sc1
	global_load_dwordx4 v[240:243], v250, s[100:101] offset:2048 sc0 sc1
	global_load_dwordx4 v[244:247], v250, s[100:101] offset:3072 sc0 sc1
	s_add_u32 s100, s100, 0x1000
	s_addc_u32 s101, s101, 0
	s_waitcnt vmcnt(0)
	v_pk_add_f32 v[32:33], v[32:33], v[232:233]
	v_pk_add_f32 v[34:35], v[34:35], v[234:235]
	v_pk_add_f32 v[36:37], v[36:37], v[236:237]
	v_pk_add_f32 v[38:39], v[38:39], v[238:239]
	v_pk_add_f32 v[40:41], v[40:41], v[240:241]
	v_pk_add_f32 v[42:43], v[42:43], v[242:243]
	v_pk_add_f32 v[44:45], v[44:45], v[244:245]
	v_pk_add_f32 v[46:47], v[46:47], v[246:247]
	global_load_dwordx4 v[232:235], v250, s[100:101] sc0 sc1
	global_load_dwordx4 v[236:239], v250, s[100:101] offset:1024 sc0 sc1
	global_load_dwordx4 v[240:243], v250, s[100:101] offset:2048 sc0 sc1
	global_load_dwordx4 v[244:247], v250, s[100:101] offset:3072 sc0 sc1
	s_add_u32 s100, s100, 0x1000
	s_addc_u32 s101, s101, 0
	s_waitcnt vmcnt(0)
	v_pk_add_f32 v[48:49], v[48:49], v[232:233]
	v_pk_add_f32 v[50:51], v[50:51], v[234:235]
	v_pk_add_f32 v[52:53], v[52:53], v[236:237]
	v_pk_add_f32 v[54:55], v[54:55], v[238:239]
	v_pk_add_f32 v[56:57], v[56:57], v[240:241]
	v_pk_add_f32 v[58:59], v[58:59], v[242:243]
	v_pk_add_f32 v[60:61], v[60:61], v[244:245]
	v_pk_add_f32 v[62:63], v[62:63], v[246:247]
	global_load_dwordx4 v[232:235], v250, s[100:101] sc0 sc1
	global_load_dwordx4 v[236:239], v250, s[100:101] offset:1024 sc0 sc1
	global_load_dwordx4 v[240:243], v250, s[100:101] offset:2048 sc0 sc1
	global_load_dwordx4 v[244:247], v250, s[100:101] offset:3072 sc0 sc1
	s_add_u32 s100, s100, 0x1000
	s_addc_u32 s101, s101, 0
	s_waitcnt vmcnt(0)
	v_pk_add_f32 v[64:65], v[64:65], v[232:233]
	v_pk_add_f32 v[66:67], v[66:67], v[234:235]
	v_pk_add_f32 v[68:69], v[68:69], v[236:237]
	v_pk_add_f32 v[70:71], v[70:71], v[238:239]
	v_pk_add_f32 v[72:73], v[72:73], v[240:241]
	v_pk_add_f32 v[74:75], v[74:75], v[242:243]
	v_pk_add_f32 v[76:77], v[76:77], v[244:245]
	v_pk_add_f32 v[78:79], v[78:79], v[246:247]
	global_load_dwordx4 v[232:235], v250, s[100:101] sc0 sc1
	global_load_dwordx4 v[236:239], v250, s[100:101] offset:1024 sc0 sc1
	global_load_dwordx4 v[240:243], v250, s[100:101] offset:2048 sc0 sc1
	global_load_dwordx4 v[244:247], v250, s[100:101] offset:3072 sc0 sc1
	s_add_u32 s100, s100, 0x1000
	s_addc_u32 s101, s101, 0
	s_waitcnt vmcnt(0)
	v_pk_add_f32 v[80:81], v[80:81], v[232:233]
	v_pk_add_f32 v[82:83], v[82:83], v[234:235]
	v_pk_add_f32 v[84:85], v[84:85], v[236:237]
	v_pk_add_f32 v[86:87], v[86:87], v[238:239]
	v_pk_add_f32 v[88:89], v[88:89], v[240:241]
	v_pk_add_f32 v[90:91], v[90:91], v[242:243]
	v_pk_add_f32 v[92:93], v[92:93], v[244:245]
	v_pk_add_f32 v[94:95], v[94:95], v[246:247]
	global_load_dwordx4 v[232:235], v250, s[100:101] sc0 sc1
	global_load_dwordx4 v[236:239], v250, s[100:101] offset:1024 sc0 sc1
	global_load_dwordx4 v[240:243], v250, s[100:101] offset:2048 sc0 sc1
	global_load_dwordx4 v[244:247], v250, s[100:101] offset:3072 sc0 sc1
	s_add_u32 s100, s100, 0x1000
	s_addc_u32 s101, s101, 0
	s_waitcnt vmcnt(0)
	v_pk_add_f32 v[96:97], v[96:97], v[232:233]
	v_pk_add_f32 v[98:99], v[98:99], v[234:235]
	v_pk_add_f32 v[100:101], v[100:101], v[236:237]
	v_pk_add_f32 v[102:103], v[102:103], v[238:239]
	v_pk_add_f32 v[104:105], v[104:105], v[240:241]
	v_pk_add_f32 v[106:107], v[106:107], v[242:243]
	v_pk_add_f32 v[108:109], v[108:109], v[244:245]
	v_pk_add_f32 v[110:111], v[110:111], v[246:247]
	global_load_dwordx4 v[232:235], v250, s[100:101] sc0 sc1
	global_load_dwordx4 v[236:239], v250, s[100:101] offset:1024 sc0 sc1
	global_load_dwordx4 v[240:243], v250, s[100:101] offset:2048 sc0 sc1
	global_load_dwordx4 v[244:247], v250, s[100:101] offset:3072 sc0 sc1
	s_add_u32 s100, s100, 0x1000
	s_addc_u32 s101, s101, 0
	s_waitcnt vmcnt(0)
	v_pk_add_f32 v[112:113], v[112:113], v[232:233]
	v_pk_add_f32 v[114:115], v[114:115], v[234:235]
	v_pk_add_f32 v[116:117], v[116:117], v[236:237]
	v_pk_add_f32 v[118:119], v[118:119], v[238:239]
	v_pk_add_f32 v[120:121], v[120:121], v[240:241]
	v_pk_add_f32 v[122:123], v[122:123], v[242:243]
	v_pk_add_f32 v[124:125], v[124:125], v[244:245]
	v_pk_add_f32 v[126:127], v[126:127], v[246:247]
